# MIX: the 128 sample scans are assigned statically to workgroups 0..127 (no atomic fetch before the critical chain); all other items from the dynamic queue
# speedup vs baseline: 1.0159x; 1.0046x over previous
.LBB0_98:
	s_and_b64 vcc, exec, s[0:1]
	s_cbranch_vccz .LBB0_146
	s_ashr_i32 s71, s70, 31
	s_lshl_b64 s[0:1], s[70:71], 2
	v_readlane_b32 s2, v255, 15
	v_readlane_b32 s3, v255, 16
	s_add_u32 s36, s2, s0
	s_addc_u32 s37, s3, s1
	s_lshl_b32 s26, s70, 7
	s_mul_i32 s28, s70, 0x920000
	s_ashr_i32 s27, s26, 31
	v_readlane_b32 s2, v254, 37
	s_mul_hi_i32 s25, s70, 0x920000
	s_add_u32 s4, s2, s28
	v_readlane_b32 s2, v254, 38
	s_addc_u32 s5, s2, s25
	v_writelane_b32 v255, s4, 38
	v_readlane_b32 s2, v254, 45
	v_readlane_b32 s3, v254, 46
	v_writelane_b32 v255, s5, 39
	v_writelane_b32 v255, s16, 40
	v_writelane_b32 v255, s18, 42
	s_add_u32 s2, s2, s0
	s_addc_u32 s3, s3, s1
	v_writelane_b32 v255, s19, 43
	v_readlane_b32 s4, v252, 49
	s_lshl_b64 s[0:1], s[26:27], 2
	v_readlane_b32 s12, v252, 57
	v_readlane_b32 s13, v252, 58
	s_add_u32 s12, s12, s0
	s_addc_u32 s13, s13, s1
	s_add_u32 s0, s96, s28
	v_readlane_b32 s14, v252, 59
	v_readlane_b32 s18, v252, 63
	v_readlane_b32 s19, v253, 0
	s_addc_u32 s1, s97, s25
	v_readlane_b32 s15, v252, 60
	v_readlane_b32 s16, v252, 61
	v_readlane_b32 s18, v255, 42
	s_add_u32 s14, s0, 0x5f34000
	s_mov_b32 s0, s70
	v_readlane_b32 s8, v252, 53
	v_readlane_b32 s9, v252, 54
	v_readlane_b32 s10, v252, 55
	v_readlane_b32 s11, v252, 56
	v_readlane_b32 s19, v255, 43
	v_readlane_b32 s16, v255, 40
	s_addc_u32 s15, s1, 0
	v_writelane_b32 v255, s0, 44
	s_mov_b64 s[10:11], s[2:3]
	s_mov_b64 s[8:9], s[36:37]
	v_writelane_b32 v255, s1, 45
	v_readlane_b32 s5, v252, 50
	v_readlane_b32 s6, v252, 51
	v_readlane_b32 s7, v252, 52
	v_readlane_b32 s17, v252, 62
	v_readlane_b32 s101, v252, 0
	s_mov_b32 s98, 1
	s_mov_b32 s99, 1
	s_mov_b32 s100, 0
	s_cmpk_lt_u32 s101, 0x80
	s_cbranch_scc0 .Lq_init_done
	s_mov_b32 s25, s101
	s_branch .Lq_go
